# FFN-down residual epilogue: the 12 gnext/scale/shift loads of the normalised store issued in one batch with exact recomputed counted waits (was 5 dependent rounds)
# speedup vs baseline: 1.0065x; 1.0065x over previous
.LBB0_291:
	s_and_b64 vcc, exec, s[0:1]
	s_cbranch_vccz .LBB0_293
	s_add_i32 s4, s8, 0x1800
	s_and_b64 s[0:1], s[10:11], exec
	s_cselect_b32 s0, s4, 0
	s_ashr_i32 s1, s0, 31
	s_lshl_b64 s[0:1], s[0:1], 2
	s_add_u32 s0, s62, s0
	s_addc_u32 s1, s63, s1
	s_add_u32 s8, s0, 0x1000
	s_addc_u32 s9, s1, 0
	v_lshlrev_b64 v[8:9], 2, v[146:147]
	v_lshl_add_u64 v[4:5], s[8:9], 0, v[8:9]
	v_lshl_add_u64 v[160:161], s[14:15], 0, v[8:9]
	global_load_dwordx4 v[4:7], v[4:5], off
	v_lshl_add_u64 v[164:165], s[0:1], 0, v[8:9]
	global_load_dwordx4 v[0:3], v[160:161], off
	v_or_b32_e32 v8, 16, v146
	v_ashrrev_i32_e32 v9, 31, v8
	v_lshl_add_u64 v[8:9], v[8:9], 2, s[8:9]
	global_load_dwordx4 v[8:11], v[8:9], off
	v_or_b32_e32 v12, 0x80, v146
	v_ashrrev_i32_e32 v13, 31, v12
	v_lshl_add_u64 v[12:13], v[12:13], 2, s[8:9]
	global_load_dwordx4 v[12:15], v[12:13], off
	v_or_b32_e32 v166, 0x90, v146
	v_ashrrev_i32_e32 v167, 31, v166
	v_lshlrev_b64 v[146:147], 1, v[146:147]
	global_load_dwordx4 v[214:217], v[160:161], off offset:64
	global_load_dwordx4 v[218:221], v[164:165], off
	global_load_dwordx4 v[222:225], v[160:161], off offset:512
	global_load_dwordx4 v[226:229], v[164:165], off offset:64
	global_load_dwordx4 v[230:233], v[160:161], off offset:576
	v_lshl_add_u64 v[250:251], v[166:167], 2, s[8:9]
	global_load_dwordx4 v[234:237], v[250:251], off
	global_load_dwordx4 v[238:241], v[164:165], off offset:512
	global_load_dwordx4 v[242:245], v[164:165], off offset:576
	s_waitcnt vmcnt(11)
	v_pk_add_f32 v[6:7], v[6:7], 1.0 op_sel_hi:[1,0]
	v_pk_add_f32 v[4:5], v[4:5], 1.0 op_sel_hi:[1,0]
	s_waitcnt vmcnt(10)
	v_pk_mul_f32 v[142:143], v[2:3], v[6:7]
	v_pk_mul_f32 v[144:145], v[0:1], v[4:5]
	s_waitcnt vmcnt(9)
	v_pk_add_f32 v[10:11], v[10:11], 1.0 op_sel_hi:[1,0]
	v_pk_add_f32 v[8:9], v[8:9], 1.0 op_sel_hi:[1,0]
	s_waitcnt vmcnt(8)
	v_pk_add_f32 v[14:15], v[14:15], 1.0 op_sel_hi:[1,0]
	v_pk_add_f32 v[12:13], v[12:13], 1.0 op_sel_hi:[1,0]
	s_waitcnt vmcnt(7)
	v_pk_mul_f32 v[152:153], v[216:217], v[10:11]
	v_pk_mul_f32 v[154:155], v[214:215], v[8:9]
	s_waitcnt vmcnt(5)
	v_pk_mul_f32 v[156:157], v[224:225], v[14:15]
	v_pk_mul_f32 v[158:159], v[222:223], v[12:13]
	v_lshl_add_u64 v[160:161], v[166:167], 2, s[8:9]
	s_waitcnt vmcnt(2)
	v_pk_add_f32 v[160:161], v[236:237], 1.0 op_sel_hi:[1,0]
	v_pk_add_f32 v[166:167], v[234:235], 1.0 op_sel_hi:[1,0]
	v_pk_mul_f32 v[160:161], v[232:233], v[160:161]
	v_pk_mul_f32 v[170:171], v[230:231], v[166:167]
	v_add_u32_e32 v172, s61, v113
	v_lshl_add_u32 v113, v113, 2, 0
	v_add_u32_e32 v113, 0x1000, v113
	ds_read2_b32 v[174:175], v113 offset1:16
	v_ashrrev_i32_e32 v173, 31, v172
	v_lshlrev_b64 v[164:165], 11, v[172:173]
	v_lshl_add_u64 v[164:165], s[6:7], 0, v[164:165]
	v_lshl_add_u64 v[164:165], v[164:165], 0, v[146:147]
	s_waitcnt lgkmcnt(0)
	v_pk_mul_f32 v[118:119], v[118:119], v[174:175] op_sel_hi:[1,0]
	v_pk_mul_f32 v[120:121], v[120:121], v[174:175] op_sel_hi:[1,0]
	s_waitcnt vmcnt(1)
	v_pk_fma_f32 v[118:119], v[158:159], v[118:119], v[238:239]
	v_pk_fma_f32 v[120:121], v[156:157], v[120:121], v[240:241]
	v_cvt_pk_bf16_f32 v118, v118, v119
	v_cvt_pk_bf16_f32 v119, v120, v121
	global_store_dwordx2 v[164:165], v[118:119], off offset:256
	v_pk_mul_f32 v[118:119], v[150:151], v[174:175] op_sel_hi:[1,0]
	v_pk_mul_f32 v[120:121], v[148:149], v[174:175] op_sel_hi:[1,0]
	v_pk_mul_f32 v[126:127], v[126:127], v[174:175] op_sel_hi:[1,0]
	v_pk_mul_f32 v[128:129], v[128:129], v[174:175] op_sel_hi:[1,0]
	v_pk_fma_f32 v[126:127], v[144:145], v[126:127], v[218:219]
	v_pk_fma_f32 v[128:129], v[142:143], v[128:129], v[220:221]
	v_pk_mul_f32 v[122:123], v[122:123], v[174:175] op_sel_hi:[1,0]
	v_pk_mul_f32 v[124:125], v[124:125], v[174:175] op_sel_hi:[1,0]
	v_pk_fma_f32 v[122:123], v[154:155], v[122:123], v[226:227]
	v_pk_fma_f32 v[124:125], v[152:153], v[124:125], v[228:229]
	v_cvt_pk_bf16_f32 v126, v126, v127
	v_cvt_pk_bf16_f32 v127, v128, v129
	v_cvt_pk_bf16_f32 v122, v122, v123
	v_cvt_pk_bf16_f32 v123, v124, v125
	global_store_dwordx2 v[164:165], v[126:127], off
	global_store_dwordx2 v[164:165], v[122:123], off offset:32
	s_waitcnt vmcnt(3)
	v_pk_fma_f32 v[120:121], v[160:161], v[120:121], v[244:245]
	v_pk_fma_f32 v[118:119], v[170:171], v[118:119], v[242:243]
	s_nop 0
	v_cvt_pk_bf16_f32 v118, v118, v119
	v_cvt_pk_bf16_f32 v119, v120, v121
	v_mov_b32_e32 v120, v175
	global_store_dwordx2 v[164:165], v[118:119], off offset:288
	v_add_u32_e32 v118, 16, v172
	v_pk_mul_f32 v[92:93], v[92:93], v[120:121] op_sel_hi:[1,0]
	v_pk_mul_f32 v[94:95], v[94:95], v[120:121] op_sel_hi:[1,0]
	v_ashrrev_i32_e32 v119, 31, v118
	v_pk_fma_f32 v[94:95], v[160:161], v[94:95], v[244:245]
	v_pk_fma_f32 v[92:93], v[170:171], v[92:93], v[242:243]
	v_lshlrev_b64 v[118:119], 11, v[118:119]
	v_cvt_pk_bf16_f32 v92, v92, v93
	v_cvt_pk_bf16_f32 v93, v94, v95
	ds_read2_b32 v[94:95], v113 offset0:32 offset1:48
	v_lshl_add_u64 v[118:119], s[6:7], 0, v[118:119]
	v_lshl_add_u64 v[118:119], v[118:119], 0, v[146:147]
	global_store_dwordx2 v[118:119], v[92:93], off offset:288
	v_add_u32_e32 v92, 32, v172
	v_ashrrev_i32_e32 v93, 31, v92
	v_lshlrev_b64 v[92:93], 11, v[92:93]
	s_waitcnt lgkmcnt(0)
	v_pk_mul_f32 v[76:77], v[76:77], v[94:95] op_sel_hi:[1,0]
	v_pk_mul_f32 v[78:79], v[78:79], v[94:95] op_sel_hi:[1,0]
	v_lshl_add_u64 v[92:93], s[6:7], 0, v[92:93]
	v_pk_fma_f32 v[78:79], v[160:161], v[78:79], v[244:245]
	v_pk_fma_f32 v[76:77], v[170:171], v[76:77], v[242:243]
	v_lshl_add_u64 v[92:93], v[92:93], 0, v[146:147]
	v_cvt_pk_bf16_f32 v76, v76, v77
	v_cvt_pk_bf16_f32 v77, v78, v79
	v_mov_b32_e32 v78, v95
	global_store_dwordx2 v[92:93], v[76:77], off offset:288
	v_add_u32_e32 v76, 48, v172
	v_pk_mul_f32 v[64:65], v[64:65], v[78:79] op_sel_hi:[1,0]
	v_pk_mul_f32 v[66:67], v[66:67], v[78:79] op_sel_hi:[1,0]
	v_ashrrev_i32_e32 v77, 31, v76
	v_pk_fma_f32 v[66:67], v[160:161], v[66:67], v[244:245]
	v_pk_fma_f32 v[64:65], v[170:171], v[64:65], v[242:243]
	v_lshlrev_b64 v[76:77], 11, v[76:77]
	v_cvt_pk_bf16_f32 v64, v64, v65
	v_cvt_pk_bf16_f32 v65, v66, v67
	ds_read2_b32 v[66:67], v113 offset0:128 offset1:144
	v_lshl_add_u64 v[76:77], s[6:7], 0, v[76:77]
	v_lshl_add_u64 v[76:77], v[76:77], 0, v[146:147]
	global_store_dwordx2 v[76:77], v[64:65], off offset:288
	v_add_u32_e32 v64, 0x80, v172
	v_ashrrev_i32_e32 v65, 31, v64
	v_lshlrev_b64 v[64:65], 11, v[64:65]
	s_waitcnt lgkmcnt(0)
	v_pk_mul_f32 v[44:45], v[44:45], v[66:67] op_sel_hi:[1,0]
	v_pk_mul_f32 v[46:47], v[46:47], v[66:67] op_sel_hi:[1,0]
	v_lshl_add_u64 v[64:65], s[6:7], 0, v[64:65]
	v_pk_fma_f32 v[46:47], v[160:161], v[46:47], v[244:245]
	v_pk_fma_f32 v[44:45], v[170:171], v[44:45], v[242:243]
	v_lshl_add_u64 v[64:65], v[64:65], 0, v[146:147]
	v_cvt_pk_bf16_f32 v44, v44, v45
	v_cvt_pk_bf16_f32 v45, v46, v47
	v_mov_b32_e32 v46, v67
	global_store_dwordx2 v[64:65], v[44:45], off offset:288
	v_add_u32_e32 v44, 0x90, v172
	v_pk_mul_f32 v[28:29], v[28:29], v[46:47] op_sel_hi:[1,0]
	v_pk_mul_f32 v[30:31], v[30:31], v[46:47] op_sel_hi:[1,0]
	v_ashrrev_i32_e32 v45, 31, v44
	v_pk_fma_f32 v[30:31], v[160:161], v[30:31], v[244:245]
	v_pk_fma_f32 v[28:29], v[170:171], v[28:29], v[242:243]
	v_lshlrev_b64 v[44:45], 11, v[44:45]
	v_cvt_pk_bf16_f32 v28, v28, v29
	v_cvt_pk_bf16_f32 v29, v30, v31
	ds_read2_b32 v[30:31], v113 offset0:160 offset1:176
	v_lshl_add_u64 v[44:45], s[6:7], 0, v[44:45]
	v_lshl_add_u64 v[44:45], v[44:45], 0, v[146:147]
	global_store_dwordx2 v[44:45], v[28:29], off offset:288
	v_add_u32_e32 v28, 0xa0, v172
	v_ashrrev_i32_e32 v29, 31, v28
	v_pk_mul_f32 v[84:85], v[84:85], v[94:95] op_sel_hi:[1,0]
	v_pk_mul_f32 v[86:87], v[86:87], v[94:95] op_sel_hi:[1,0]
	v_lshlrev_b64 v[28:29], 11, v[28:29]
	s_waitcnt lgkmcnt(0)
	v_pk_mul_f32 v[20:21], v[20:21], v[30:31] op_sel_hi:[1,0]
	v_pk_mul_f32 v[22:23], v[22:23], v[30:31] op_sel_hi:[1,0]
	v_pk_fma_f32 v[86:87], v[156:157], v[86:87], v[240:241]
	v_pk_fma_f32 v[84:85], v[158:159], v[84:85], v[238:239]
	v_lshl_add_u64 v[28:29], s[6:7], 0, v[28:29]
	v_pk_fma_f32 v[22:23], v[156:157], v[22:23], v[240:241]
	v_pk_fma_f32 v[20:21], v[158:159], v[20:21], v[238:239]
	v_cvt_pk_bf16_f32 v84, v84, v85
	v_cvt_pk_bf16_f32 v85, v86, v87
	v_lshl_add_u64 v[28:29], v[28:29], 0, v[146:147]
	v_cvt_pk_bf16_f32 v20, v20, v21
	v_cvt_pk_bf16_f32 v21, v22, v23
	global_store_dwordx2 v[92:93], v[84:85], off offset:256
	global_store_dwordx2 v[28:29], v[20:21], off offset:256
	v_pk_mul_f32 v[20:21], v[116:117], v[30:31] op_sel_hi:[1,0]
	v_pk_mul_f32 v[22:23], v[114:115], v[30:31] op_sel_hi:[1,0]
	v_pk_fma_f32 v[20:21], v[170:171], v[20:21], v[242:243]
	v_pk_fma_f32 v[22:23], v[160:161], v[22:23], v[244:245]
	v_cvt_pk_bf16_f32 v20, v20, v21
	v_cvt_pk_bf16_f32 v21, v22, v23
	global_store_dwordx2 v[28:29], v[20:21], off offset:288
	v_add_u32_e32 v20, 0xb0, v172
	v_ashrrev_i32_e32 v21, 31, v20
	v_mov_b32_e32 v22, v31
	v_pk_mul_f32 v[110:111], v[110:111], v[120:121] op_sel_hi:[1,0]
	v_pk_mul_f32 v[108:109], v[108:109], v[120:121] op_sel_hi:[1,0]
	v_pk_mul_f32 v[96:97], v[96:97], v[94:95] op_sel_hi:[1,0]
	v_pk_mul_f32 v[98:99], v[98:99], v[94:95] op_sel_hi:[1,0]
	v_pk_mul_f32 v[80:81], v[80:81], v[78:79] op_sel_hi:[1,0]
	v_pk_mul_f32 v[82:83], v[82:83], v[78:79] op_sel_hi:[1,0]
	v_pk_mul_f32 v[60:61], v[60:61], v[66:67] op_sel_hi:[1,0]
	v_pk_mul_f32 v[62:63], v[62:63], v[66:67] op_sel_hi:[1,0]
	v_pk_mul_f32 v[48:49], v[48:49], v[46:47] op_sel_hi:[1,0]
	v_pk_mul_f32 v[50:51], v[50:51], v[46:47] op_sel_hi:[1,0]
	v_pk_mul_f32 v[32:33], v[32:33], v[30:31] op_sel_hi:[1,0]
	v_pk_mul_f32 v[34:35], v[34:35], v[30:31] op_sel_hi:[1,0]
	v_lshlrev_b64 v[20:21], 11, v[20:21]
	v_pk_mul_f32 v[16:17], v[16:17], v[22:23] op_sel_hi:[1,0]
	v_pk_mul_f32 v[18:19], v[18:19], v[22:23] op_sel_hi:[1,0]
	v_pk_fma_f32 v[108:109], v[142:143], v[108:109], v[220:221]
	v_pk_fma_f32 v[110:111], v[144:145], v[110:111], v[218:219]
	v_pk_fma_f32 v[98:99], v[142:143], v[98:99], v[220:221]
	v_pk_fma_f32 v[96:97], v[144:145], v[96:97], v[218:219]
	v_pk_fma_f32 v[82:83], v[142:143], v[82:83], v[220:221]
	v_pk_fma_f32 v[80:81], v[144:145], v[80:81], v[218:219]
	v_pk_fma_f32 v[62:63], v[142:143], v[62:63], v[220:221]
	v_pk_fma_f32 v[60:61], v[144:145], v[60:61], v[218:219]
	v_pk_fma_f32 v[50:51], v[142:143], v[50:51], v[220:221]
	v_pk_fma_f32 v[48:49], v[144:145], v[48:49], v[218:219]
	v_pk_fma_f32 v[34:35], v[142:143], v[34:35], v[220:221]
	v_pk_fma_f32 v[32:33], v[144:145], v[32:33], v[218:219]
	v_lshl_add_u64 v[20:21], s[6:7], 0, v[20:21]
	v_pk_fma_f32 v[2:3], v[142:143], v[18:19], v[220:221]
	v_pk_fma_f32 v[0:1], v[144:145], v[16:17], v[218:219]
	v_cvt_pk_bf16_f32 v80, v80, v81
	v_cvt_pk_bf16_f32 v81, v82, v83
	v_lshl_add_u64 v[20:21], v[20:21], 0, v[146:147]
	v_cvt_pk_bf16_f32 v0, v0, v1
	v_cvt_pk_bf16_f32 v1, v2, v3
	global_store_dwordx2 v[76:77], v[80:81], off
	v_pk_mul_f32 v[72:73], v[72:73], v[78:79] op_sel_hi:[1,0]
	v_pk_mul_f32 v[74:75], v[74:75], v[78:79] op_sel_hi:[1,0]
	global_store_dwordx2 v[20:21], v[0:1], off
	v_pk_mul_f32 v[0:1], v[138:139], v[22:23] op_sel_hi:[1,0]
	v_pk_mul_f32 v[2:3], v[140:141], v[22:23] op_sel_hi:[1,0]
	v_pk_fma_f32 v[74:75], v[152:153], v[74:75], v[228:229]
	v_pk_fma_f32 v[72:73], v[154:155], v[72:73], v[226:227]
	v_pk_fma_f32 v[2:3], v[152:153], v[2:3], v[228:229]
	v_pk_fma_f32 v[0:1], v[154:155], v[0:1], v[226:227]
	v_cvt_pk_bf16_f32 v72, v72, v73
	v_cvt_pk_bf16_f32 v73, v74, v75
	v_cvt_pk_bf16_f32 v0, v0, v1
	v_cvt_pk_bf16_f32 v1, v2, v3
	global_store_dwordx2 v[76:77], v[72:73], off offset:32
	v_pk_mul_f32 v[68:69], v[68:69], v[78:79] op_sel_hi:[1,0]
	v_pk_mul_f32 v[70:71], v[70:71], v[78:79] op_sel_hi:[1,0]
	global_store_dwordx2 v[20:21], v[0:1], off offset:32
	v_pk_mul_f32 v[0:1], v[134:135], v[22:23] op_sel_hi:[1,0]
	v_pk_mul_f32 v[2:3], v[136:137], v[22:23] op_sel_hi:[1,0]
	v_pk_fma_f32 v[70:71], v[156:157], v[70:71], v[240:241]
	v_pk_fma_f32 v[68:69], v[158:159], v[68:69], v[238:239]
	v_pk_fma_f32 v[2:3], v[156:157], v[2:3], v[240:241]
	v_pk_fma_f32 v[0:1], v[158:159], v[0:1], v[238:239]
	v_cvt_pk_bf16_f32 v68, v68, v69
	v_cvt_pk_bf16_f32 v69, v70, v71
	v_cvt_pk_bf16_f32 v0, v0, v1
	v_cvt_pk_bf16_f32 v1, v2, v3
	v_pk_mul_f32 v[104:105], v[104:105], v[120:121] op_sel_hi:[1,0]
	v_pk_mul_f32 v[106:107], v[106:107], v[120:121] op_sel_hi:[1,0]
	v_pk_mul_f32 v[100:101], v[100:101], v[120:121] op_sel_hi:[1,0]
	v_pk_mul_f32 v[102:103], v[102:103], v[120:121] op_sel_hi:[1,0]
	v_pk_mul_f32 v[88:89], v[88:89], v[94:95] op_sel_hi:[1,0]
	v_pk_mul_f32 v[90:91], v[90:91], v[94:95] op_sel_hi:[1,0]
	global_store_dwordx2 v[76:77], v[68:69], off offset:256
	v_pk_mul_f32 v[56:57], v[56:57], v[66:67] op_sel_hi:[1,0]
	v_pk_mul_f32 v[58:59], v[58:59], v[66:67] op_sel_hi:[1,0]
	v_pk_mul_f32 v[52:53], v[52:53], v[66:67] op_sel_hi:[1,0]
	v_pk_mul_f32 v[54:55], v[54:55], v[66:67] op_sel_hi:[1,0]
	v_pk_mul_f32 v[40:41], v[40:41], v[46:47] op_sel_hi:[1,0]
	v_pk_mul_f32 v[42:43], v[42:43], v[46:47] op_sel_hi:[1,0]
	v_pk_mul_f32 v[36:37], v[36:37], v[46:47] op_sel_hi:[1,0]
	v_pk_mul_f32 v[38:39], v[38:39], v[46:47] op_sel_hi:[1,0]
	v_pk_mul_f32 v[24:25], v[24:25], v[30:31] op_sel_hi:[1,0]
	v_pk_mul_f32 v[26:27], v[26:27], v[30:31] op_sel_hi:[1,0]
	global_store_dwordx2 v[20:21], v[0:1], off offset:256
	v_pk_mul_f32 v[0:1], v[130:131], v[22:23] op_sel_hi:[1,0]
	v_pk_mul_f32 v[2:3], v[132:133], v[22:23] op_sel_hi:[1,0]
	v_pk_fma_f32 v[106:107], v[152:153], v[106:107], v[228:229]
	v_pk_fma_f32 v[104:105], v[154:155], v[104:105], v[226:227]
	v_pk_fma_f32 v[102:103], v[156:157], v[102:103], v[240:241]
	v_pk_fma_f32 v[100:101], v[158:159], v[100:101], v[238:239]
	v_pk_fma_f32 v[90:91], v[152:153], v[90:91], v[228:229]
	v_pk_fma_f32 v[88:89], v[154:155], v[88:89], v[226:227]
	v_pk_fma_f32 v[58:59], v[152:153], v[58:59], v[228:229]
	v_pk_fma_f32 v[56:57], v[154:155], v[56:57], v[226:227]
	v_pk_fma_f32 v[54:55], v[156:157], v[54:55], v[240:241]
	v_pk_fma_f32 v[52:53], v[158:159], v[52:53], v[238:239]
	v_pk_fma_f32 v[42:43], v[152:153], v[42:43], v[228:229]
	v_pk_fma_f32 v[40:41], v[154:155], v[40:41], v[226:227]
	v_pk_fma_f32 v[38:39], v[156:157], v[38:39], v[240:241]
	v_pk_fma_f32 v[36:37], v[158:159], v[36:37], v[238:239]
	v_pk_fma_f32 v[26:27], v[152:153], v[26:27], v[228:229]
	v_pk_fma_f32 v[24:25], v[154:155], v[24:25], v[226:227]
	v_pk_fma_f32 v[2:3], v[160:161], v[2:3], v[244:245]
	v_pk_fma_f32 v[0:1], v[170:171], v[0:1], v[242:243]
	v_cvt_pk_bf16_f32 v110, v110, v111
	v_cvt_pk_bf16_f32 v111, v108, v109
	v_cvt_pk_bf16_f32 v104, v104, v105
	v_cvt_pk_bf16_f32 v105, v106, v107
	v_cvt_pk_bf16_f32 v100, v100, v101
	v_cvt_pk_bf16_f32 v101, v102, v103
	v_cvt_pk_bf16_f32 v96, v96, v97
	v_cvt_pk_bf16_f32 v97, v98, v99
	v_cvt_pk_bf16_f32 v88, v88, v89
	v_cvt_pk_bf16_f32 v89, v90, v91
	v_cvt_pk_bf16_f32 v60, v60, v61
	v_cvt_pk_bf16_f32 v61, v62, v63
	v_cvt_pk_bf16_f32 v56, v56, v57
	v_cvt_pk_bf16_f32 v57, v58, v59
	v_cvt_pk_bf16_f32 v52, v52, v53
	v_cvt_pk_bf16_f32 v53, v54, v55
	v_cvt_pk_bf16_f32 v48, v48, v49
	v_cvt_pk_bf16_f32 v49, v50, v51
	v_cvt_pk_bf16_f32 v40, v40, v41
	v_cvt_pk_bf16_f32 v41, v42, v43
	v_cvt_pk_bf16_f32 v36, v36, v37
	v_cvt_pk_bf16_f32 v37, v38, v39
	v_cvt_pk_bf16_f32 v32, v32, v33
	v_cvt_pk_bf16_f32 v33, v34, v35
	v_cvt_pk_bf16_f32 v24, v24, v25
	v_cvt_pk_bf16_f32 v25, v26, v27
	v_cvt_pk_bf16_f32 v0, v0, v1
	v_cvt_pk_bf16_f32 v1, v2, v3
	global_store_dwordx2 v[118:119], v[110:111], off
	global_store_dwordx2 v[118:119], v[104:105], off offset:32
	global_store_dwordx2 v[118:119], v[100:101], off offset:256
	global_store_dwordx2 v[92:93], v[96:97], off
	global_store_dwordx2 v[92:93], v[88:89], off offset:32
	global_store_dwordx2 v[64:65], v[60:61], off
	global_store_dwordx2 v[64:65], v[56:57], off offset:32
	global_store_dwordx2 v[64:65], v[52:53], off offset:256
	global_store_dwordx2 v[44:45], v[48:49], off
	global_store_dwordx2 v[44:45], v[40:41], off offset:32
	global_store_dwordx2 v[44:45], v[36:37], off offset:256
	global_store_dwordx2 v[28:29], v[32:33], off
	global_store_dwordx2 v[28:29], v[24:25], off offset:32
	global_store_dwordx2 v[20:21], v[0:1], off offset:288
	v_mov_b32_e32 v4, v226
	v_mov_b32_e32 v5, v227
	v_mov_b32_e32 v6, v228
	v_mov_b32_e32 v7, v229
	v_mov_b32_e32 v8, v238
	v_mov_b32_e32 v9, v239
	v_mov_b32_e32 v10, v240
	v_mov_b32_e32 v11, v241
	v_mov_b32_e32 v12, v242
	v_mov_b32_e32 v13, v243
	v_mov_b32_e32 v14, v244
	v_mov_b32_e32 v15, v245
